# grid barrier: non-leader workgroups poll the top-level generation word directly instead of the per-XCD release word (one fewer hop)
# speedup vs baseline: 1.0017x; 1.0017x over previous
; __device__ __forceinline__ unsigned xb_ld(unsigned* p)              { return __hip_atomic_load(p, __ATOMIC_RELAXED, __HIP_MEMORY_SCOPE_AGENT); }
; __device__ __forceinline__ unsigned xb_add(unsigned* p, unsigned v) { return __hip_atomic_fetch_add(p, v, __ATOMIC_RELAXED, __HIP_MEMORY_SCOPE_AGENT); }
; #define XB_SPIN(cond, bar) do { unsigned _sp = 0; while (cond) { __builtin_amdgcn_s_sleep(1); \
;     if ((++_sp & 255u) == 0u) { if (xb_ld(&(bar)[XB_TMO])) break; if (_sp > XB_SPIN_CAP) { atomicAdd(&(bar)[XB_TMO], 1u); break; } } } } while (0)
; __device__ __forceinline__ void xcd_barrier(const XcdBarrier& b) {
;     ...
;         const unsigned old = xb_add(&bar[XB_XSUB(b.x)], 1u);
;         const unsigned gen = old / nloc;
;         if (old + 1u == (gen + 1u) * nloc) {
;             __builtin_amdgcn_fence(__ATOMIC_RELEASE, "agent");
;             asm volatile("s_waitcnt vmcnt(0)" ::: "memory");
;             const unsigned og = xb_add(&bar[XB_TOP], 1u);
;             const unsigned tg = og / nx;
;             if (og + 1u == (tg + 1u) * nx) xb_add(&bar[XB_TOPGEN], 1u);
;             else XB_SPIN(xb_ld(&bar[XB_TOPGEN]) == tg, bar);
;             __builtin_amdgcn_fence(__ATOMIC_ACQUIRE, "agent");
;             xb_add(&bar[XB_XGEN(b.x)], 1u);
;             asm volatile("s_waitcnt vmcnt(0)" ::: "memory");
;         } else {
;             XB_SPIN(xb_ld(&bar[XB_XGEN(b.x)]) == gen, bar);
.LBB0_1285:
	s_or_b64 exec, exec, s[4:5]
	v_cvt_f32_u32_e32 v5, v3
	s_waitcnt vmcnt(0)
	v_readfirstlane_b32 s2, v4
	v_sub_u32_e32 v4, 0, v3
	v_rcp_iflag_f32_e32 v5, v5
	v_add_u32_e32 v6, s2, v0
	v_mul_f32_e32 v5, 0x4f7ffffe, v5
	v_cvt_u32_f32_e32 v5, v5
	v_mul_lo_u32 v0, v4, v5
	v_mul_hi_u32 v0, v5, v0
	v_add_u32_e32 v0, v5, v0
	v_mul_hi_u32 v0, v6, v0
	v_mul_lo_u32 v4, v0, v3
	v_sub_u32_e32 v4, v6, v4
	v_add_u32_e32 v5, 1, v0
	v_cmp_ge_u32_e32 vcc, v4, v3
	s_nop 1
	v_cndmask_b32_e32 v0, v0, v5, vcc
	v_sub_u32_e32 v5, v4, v3
	v_cndmask_b32_e32 v4, v4, v5, vcc
	v_add_u32_e32 v5, 1, v0
	v_cmp_ge_u32_e32 vcc, v4, v3
	v_add_u32_e32 v4, 1, v6
	s_nop 0
	v_cndmask_b32_e32 v0, v0, v5, vcc
	v_mul_lo_u32 v5, v3, v0
	v_add_u32_e32 v3, v5, v3
	v_cmp_ne_u32_e32 vcc, v4, v3
	s_and_saveexec_b64 s[2:3], vcc
	s_xor_b64 s[4:5], exec, s[2:3]
	s_cbranch_execz .LBB0_1299
	v_readlane_b32 s2, v252, 23
	v_readlane_b32 s3, v252, 24
	s_waitcnt lgkmcnt(0)
	s_nop 3
	global_load_dword v2, v1, s[2:3] sc1
	s_waitcnt vmcnt(0)
	v_cmp_eq_u32_e32 vcc, v2, v0
	s_and_saveexec_b64 s[6:7], vcc
	s_cbranch_execz .LBB0_1298
	s_mov_b32 s18, 1
	s_mov_b64 s[8:9], 0
	s_branch .LBB0_1289
